# hand-written phase_ybt: loads prefetched 4 tiles ahead, rotating LDS buffers, one barrier per tile
# speedup vs baseline: 1.3623x; 1.0057x over previous
; __device__ __forceinline__ void phase_ybt(KP kp_){ asm volatile("" : "+s"(kp_)); const Params p=load_params(kp_);
;   int tid=threadIdx.x; asm volatile("" : "+v"(tid));
;   const u16* ybT=(const u16*)(p.ws+OFF_YBT); u16* yb=(u16*)(p.ws+OFF_YB);
;   u16* tile=(u16*)smem;
;   for (int it=blockIdx.x; it<4096; it+=gridDim.x){
;     int c0=(it&15)*64, t0=(it>>4)*64;
;     __syncthreads();
;     { int ch=tid>>3, t8=(tid&7)*8; *(u32x4*)(tile+ch*72+t8)=*(const u32x4*)(ybT+(size_t)(c0+ch)*16384+t0+t8); }
;     __syncthreads();
;     { int tk=tid>>3, c8=(tid&7)*8; u32x4 pk;
;       _Pragma("unroll") for (int q=0;q<4;++q) pk[q]=(unsigned)tile[(c8+2*q)*72+tk] | ((unsigned)tile[(c8+2*q+1)*72+tk]<<16);
;       *(u32x4*)(yb+(size_t)(t0+tk)*1024+c0+c8)=pk; }
;   }
; }
.LBB0_1392:
	v_readlane_b32 s48, v254, 52
	s_mov_b64 s[0:1], s[78:79]
	v_mov_b32_e32 v0, v154
	s_cmpk_gt_i32 s75, 0xfff
	v_readlane_b32 s49, v254, 53
	v_readlane_b32 s50, v254, 56
	s_cbranch_scc1 .LBB0_1395
	s_load_dwordx2 s[2:3], s[0:1], 0xe0
	v_lshrrev_b32_e32 v1, 3, v154
	v_and_b32_e32 v2, 7, v154
	v_lshlrev_b32_e32 v3, 4, v2
	s_and_b32 s4, s75, 15
	s_lshr_b32 s5, s75, 4
	s_lshl_b32 s6, s4, 6
	s_lshl_b32 s7, s5, 6
	v_add_u32_e32 v4, s6, v1
	v_lshlrev_b32_e32 v4, 15, v4
	s_lshl_b32 s8, s7, 1
	v_add3_u32 v4, v4, s8, v3
	v_add_u32_e32 v5, s7, v1
	v_lshlrev_b32_e32 v5, 11, v5
	s_lshl_b32 s8, s6, 1
	v_add3_u32 v5, v5, s8, v3
	v_mul_u32_u24_e32 v6, 0x90, v1
	v_add_u32_e32 v6, v6, v3
	v_mul_u32_u24_e32 v7, 0x480, v2
	v_lshl_add_u32 v7, v1, 1, v7
	s_waitcnt lgkmcnt(0)
	s_add_u32 s0, s2, 0x82bd000
	s_addc_u32 s1, s3, 0
	s_add_u32 s2, s2, 0x42bd000
	s_addc_u32 s3, s3, 0
	global_load_dwordx4 v[8:11], v4, s[0:1]
	s_add_u32 s8, s0, 0x800
	s_addc_u32 s9, s1, 0
	global_load_dwordx4 v[12:15], v4, s[8:9]
	s_add_u32 s8, s0, 0x1000
	s_addc_u32 s9, s1, 0
	global_load_dwordx4 v[16:19], v4, s[8:9]
	s_add_u32 s8, s0, 0x1800
	s_addc_u32 s9, s1, 0
	global_load_dwordx4 v[20:23], v4, s[8:9]
	s_barrier
	s_waitcnt vmcnt(3)
	ds_write_b128 v6, v[8:11] offset:0
	s_waitcnt lgkmcnt(0)
	s_barrier
	ds_read_u16 v24, v7 offset:0
	ds_read_u16 v25, v7 offset:144
	ds_read_u16 v26, v7 offset:288
	ds_read_u16 v27, v7 offset:432
	ds_read_u16 v28, v7 offset:576
	ds_read_u16 v29, v7 offset:720
	ds_read_u16 v30, v7 offset:864
	ds_read_u16 v31, v7 offset:1008
	s_add_u32 s8, s0, 0x2000
	s_addc_u32 s9, s1, 0
	global_load_dwordx4 v[8:11], v4, s[8:9]
	s_waitcnt lgkmcnt(0)
	v_lshl_or_b32 v32, v25, 16, v24
	v_lshl_or_b32 v33, v27, 16, v26
	v_lshl_or_b32 v34, v29, 16, v28
	v_lshl_or_b32 v35, v31, 16, v30
	global_store_dwordx4 v5, v[32:35], s[2:3]
	s_nop 1
	s_waitcnt vmcnt(4)
	ds_write_b128 v6, v[12:15] offset:9216
	s_waitcnt lgkmcnt(0)
	s_barrier
	ds_read_u16 v24, v7 offset:9216
	ds_read_u16 v25, v7 offset:9360
	ds_read_u16 v26, v7 offset:9504
	ds_read_u16 v27, v7 offset:9648
	ds_read_u16 v28, v7 offset:9792
	ds_read_u16 v29, v7 offset:9936
	ds_read_u16 v30, v7 offset:10080
	ds_read_u16 v31, v7 offset:10224
	s_add_u32 s8, s0, 0x2800
	s_addc_u32 s9, s1, 0
	global_load_dwordx4 v[12:15], v4, s[8:9]
	s_waitcnt lgkmcnt(0)
	v_lshl_or_b32 v32, v25, 16, v24
	v_lshl_or_b32 v33, v27, 16, v26
	v_lshl_or_b32 v34, v29, 16, v28
	v_lshl_or_b32 v35, v31, 16, v30
	s_add_u32 s8, s2, 0x200000
	s_addc_u32 s9, s3, 0
	global_store_dwordx4 v5, v[32:35], s[8:9]
	s_nop 1
	s_waitcnt vmcnt(5)
	ds_write_b128 v6, v[16:19] offset:18432
	s_waitcnt lgkmcnt(0)
	s_barrier
	ds_read_u16 v24, v7 offset:18432
	ds_read_u16 v25, v7 offset:18576
	ds_read_u16 v26, v7 offset:18720
	ds_read_u16 v27, v7 offset:18864
	ds_read_u16 v28, v7 offset:19008
	ds_read_u16 v29, v7 offset:19152
	ds_read_u16 v30, v7 offset:19296
	ds_read_u16 v31, v7 offset:19440
	s_add_u32 s8, s0, 0x3000
	s_addc_u32 s9, s1, 0
	global_load_dwordx4 v[16:19], v4, s[8:9]
	s_waitcnt lgkmcnt(0)
	v_lshl_or_b32 v32, v25, 16, v24
	v_lshl_or_b32 v33, v27, 16, v26
	v_lshl_or_b32 v34, v29, 16, v28
	v_lshl_or_b32 v35, v31, 16, v30
	s_add_u32 s8, s2, 0x400000
	s_addc_u32 s9, s3, 0
	global_store_dwordx4 v5, v[32:35], s[8:9]
	s_nop 1
	s_waitcnt vmcnt(6)
	ds_write_b128 v6, v[20:23] offset:27648
	s_waitcnt lgkmcnt(0)
	s_barrier
	ds_read_u16 v24, v7 offset:27648
	ds_read_u16 v25, v7 offset:27792
	ds_read_u16 v26, v7 offset:27936
	ds_read_u16 v27, v7 offset:28080
	ds_read_u16 v28, v7 offset:28224
	ds_read_u16 v29, v7 offset:28368
	ds_read_u16 v30, v7 offset:28512
	ds_read_u16 v31, v7 offset:28656
	s_add_u32 s8, s0, 0x3800
	s_addc_u32 s9, s1, 0
	global_load_dwordx4 v[20:23], v4, s[8:9]
	s_waitcnt lgkmcnt(0)
	v_lshl_or_b32 v32, v25, 16, v24
	v_lshl_or_b32 v33, v27, 16, v26
	v_lshl_or_b32 v34, v29, 16, v28
	v_lshl_or_b32 v35, v31, 16, v30
	s_add_u32 s8, s2, 0x600000
	s_addc_u32 s9, s3, 0
	global_store_dwordx4 v5, v[32:35], s[8:9]
	s_nop 1
	s_waitcnt vmcnt(7)
	ds_write_b128 v6, v[8:11] offset:0
	s_waitcnt lgkmcnt(0)
	s_barrier
	ds_read_u16 v24, v7 offset:0
	ds_read_u16 v25, v7 offset:144
	ds_read_u16 v26, v7 offset:288
	ds_read_u16 v27, v7 offset:432
	ds_read_u16 v28, v7 offset:576
	ds_read_u16 v29, v7 offset:720
	ds_read_u16 v30, v7 offset:864
	ds_read_u16 v31, v7 offset:1008
	s_add_u32 s8, s0, 0x4000
	s_addc_u32 s9, s1, 0
	global_load_dwordx4 v[8:11], v4, s[8:9]
	s_waitcnt lgkmcnt(0)
	v_lshl_or_b32 v32, v25, 16, v24
	v_lshl_or_b32 v33, v27, 16, v26
	v_lshl_or_b32 v34, v29, 16, v28
	v_lshl_or_b32 v35, v31, 16, v30
	s_add_u32 s8, s2, 0x800000
	s_addc_u32 s9, s3, 0
	global_store_dwordx4 v5, v[32:35], s[8:9]
	s_nop 1
	s_waitcnt vmcnt(7)
	ds_write_b128 v6, v[12:15] offset:9216
	s_waitcnt lgkmcnt(0)
	s_barrier
	ds_read_u16 v24, v7 offset:9216
	ds_read_u16 v25, v7 offset:9360
	ds_read_u16 v26, v7 offset:9504
	ds_read_u16 v27, v7 offset:9648
	ds_read_u16 v28, v7 offset:9792
	ds_read_u16 v29, v7 offset:9936
	ds_read_u16 v30, v7 offset:10080
	ds_read_u16 v31, v7 offset:10224
	s_add_u32 s8, s0, 0x4800
	s_addc_u32 s9, s1, 0
	global_load_dwordx4 v[12:15], v4, s[8:9]
	s_waitcnt lgkmcnt(0)
	v_lshl_or_b32 v32, v25, 16, v24
	v_lshl_or_b32 v33, v27, 16, v26
	v_lshl_or_b32 v34, v29, 16, v28
	v_lshl_or_b32 v35, v31, 16, v30
	s_add_u32 s8, s2, 0xa00000
	s_addc_u32 s9, s3, 0
	global_store_dwordx4 v5, v[32:35], s[8:9]
	s_nop 1
	s_waitcnt vmcnt(7)
	ds_write_b128 v6, v[16:19] offset:18432
	s_waitcnt lgkmcnt(0)
	s_barrier
; __device__ __forceinline__ void phase_ybt(KP kp_){ asm volatile("" : "+s"(kp_)); const Params p=load_params(kp_);
;     ...
;   for (int it=blockIdx.x; it<4096; it+=gridDim.x){
;     int c0=(it&15)*64, t0=(it>>4)*64;
;     __syncthreads();
;     { int ch=tid>>3, t8=(tid&7)*8; *(u32x4*)(tile+ch*72+t8)=*(const u32x4*)(ybT+(size_t)(c0+ch)*16384+t0+t8); }
;     __syncthreads();
;     { int tk=tid>>3, c8=(tid&7)*8; u32x4 pk;
;       _Pragma("unroll") for (int q=0;q<4;++q) pk[q]=(unsigned)tile[(c8+2*q)*72+tk] | ((unsigned)tile[(c8+2*q+1)*72+tk]<<16);
;       *(u32x4*)(yb+(size_t)(t0+tk)*1024+c0+c8)=pk; }
	ds_read_u16 v24, v7 offset:18432
	ds_read_u16 v25, v7 offset:18576
	ds_read_u16 v26, v7 offset:18720
	ds_read_u16 v27, v7 offset:18864
	ds_read_u16 v28, v7 offset:19008
	ds_read_u16 v29, v7 offset:19152
	ds_read_u16 v30, v7 offset:19296
	ds_read_u16 v31, v7 offset:19440
	s_add_u32 s8, s0, 0x5000
	s_addc_u32 s9, s1, 0
	global_load_dwordx4 v[16:19], v4, s[8:9]
	s_waitcnt lgkmcnt(0)
	v_lshl_or_b32 v32, v25, 16, v24
	v_lshl_or_b32 v33, v27, 16, v26
	v_lshl_or_b32 v34, v29, 16, v28
	v_lshl_or_b32 v35, v31, 16, v30
	s_add_u32 s8, s2, 0xc00000
	s_addc_u32 s9, s3, 0
	global_store_dwordx4 v5, v[32:35], s[8:9]
	s_nop 1
	s_waitcnt vmcnt(7)
	ds_write_b128 v6, v[20:23] offset:27648
	s_waitcnt lgkmcnt(0)
	s_barrier
	ds_read_u16 v24, v7 offset:27648
	ds_read_u16 v25, v7 offset:27792
	ds_read_u16 v26, v7 offset:27936
	ds_read_u16 v27, v7 offset:28080
	ds_read_u16 v28, v7 offset:28224
	ds_read_u16 v29, v7 offset:28368
	ds_read_u16 v30, v7 offset:28512
	ds_read_u16 v31, v7 offset:28656
	s_add_u32 s8, s0, 0x5800
	s_addc_u32 s9, s1, 0
	global_load_dwordx4 v[20:23], v4, s[8:9]
	s_waitcnt lgkmcnt(0)
	v_lshl_or_b32 v32, v25, 16, v24
	v_lshl_or_b32 v33, v27, 16, v26
	v_lshl_or_b32 v34, v29, 16, v28
	v_lshl_or_b32 v35, v31, 16, v30
	s_add_u32 s8, s2, 0xe00000
	s_addc_u32 s9, s3, 0
	global_store_dwordx4 v5, v[32:35], s[8:9]
	s_nop 1
	s_waitcnt vmcnt(7)
	ds_write_b128 v6, v[8:11] offset:0
	s_waitcnt lgkmcnt(0)
	s_barrier
	ds_read_u16 v24, v7 offset:0
	ds_read_u16 v25, v7 offset:144
	ds_read_u16 v26, v7 offset:288
	ds_read_u16 v27, v7 offset:432
	ds_read_u16 v28, v7 offset:576
	ds_read_u16 v29, v7 offset:720
	ds_read_u16 v30, v7 offset:864
	ds_read_u16 v31, v7 offset:1008
	s_add_u32 s8, s0, 0x6000
	s_addc_u32 s9, s1, 0
	global_load_dwordx4 v[8:11], v4, s[8:9]
	s_waitcnt lgkmcnt(0)
	v_lshl_or_b32 v32, v25, 16, v24
	v_lshl_or_b32 v33, v27, 16, v26
	v_lshl_or_b32 v34, v29, 16, v28
	v_lshl_or_b32 v35, v31, 16, v30
	s_add_u32 s8, s2, 0x1000000
	s_addc_u32 s9, s3, 0
	global_store_dwordx4 v5, v[32:35], s[8:9]
	s_nop 1
	s_waitcnt vmcnt(7)
	ds_write_b128 v6, v[12:15] offset:9216
	s_waitcnt lgkmcnt(0)
	s_barrier
	ds_read_u16 v24, v7 offset:9216
	ds_read_u16 v25, v7 offset:9360
	ds_read_u16 v26, v7 offset:9504
	ds_read_u16 v27, v7 offset:9648
	ds_read_u16 v28, v7 offset:9792
	ds_read_u16 v29, v7 offset:9936
	ds_read_u16 v30, v7 offset:10080
	ds_read_u16 v31, v7 offset:10224
	s_add_u32 s8, s0, 0x6800
	s_addc_u32 s9, s1, 0
	global_load_dwordx4 v[12:15], v4, s[8:9]
	s_waitcnt lgkmcnt(0)
	v_lshl_or_b32 v32, v25, 16, v24
	v_lshl_or_b32 v33, v27, 16, v26
	v_lshl_or_b32 v34, v29, 16, v28
	v_lshl_or_b32 v35, v31, 16, v30
	s_add_u32 s8, s2, 0x1200000
	s_addc_u32 s9, s3, 0
	global_store_dwordx4 v5, v[32:35], s[8:9]
	s_nop 1
	s_waitcnt vmcnt(7)
	ds_write_b128 v6, v[16:19] offset:18432
	s_waitcnt lgkmcnt(0)
	s_barrier
	ds_read_u16 v24, v7 offset:18432
	ds_read_u16 v25, v7 offset:18576
	ds_read_u16 v26, v7 offset:18720
	ds_read_u16 v27, v7 offset:18864
	ds_read_u16 v28, v7 offset:19008
	ds_read_u16 v29, v7 offset:19152
	ds_read_u16 v30, v7 offset:19296
	ds_read_u16 v31, v7 offset:19440
	s_add_u32 s8, s0, 0x7000
	s_addc_u32 s9, s1, 0
	global_load_dwordx4 v[16:19], v4, s[8:9]
	s_waitcnt lgkmcnt(0)
	v_lshl_or_b32 v32, v25, 16, v24
	v_lshl_or_b32 v33, v27, 16, v26
	v_lshl_or_b32 v34, v29, 16, v28
	v_lshl_or_b32 v35, v31, 16, v30
	s_add_u32 s8, s2, 0x1400000
	s_addc_u32 s9, s3, 0
	global_store_dwordx4 v5, v[32:35], s[8:9]
	s_nop 1
	s_waitcnt vmcnt(7)
	ds_write_b128 v6, v[20:23] offset:27648
	s_waitcnt lgkmcnt(0)
	s_barrier
	ds_read_u16 v24, v7 offset:27648
	ds_read_u16 v25, v7 offset:27792
	ds_read_u16 v26, v7 offset:27936
	ds_read_u16 v27, v7 offset:28080
	ds_read_u16 v28, v7 offset:28224
	ds_read_u16 v29, v7 offset:28368
	ds_read_u16 v30, v7 offset:28512
	ds_read_u16 v31, v7 offset:28656
	s_add_u32 s8, s0, 0x7800
	s_addc_u32 s9, s1, 0
	global_load_dwordx4 v[20:23], v4, s[8:9]
	s_waitcnt lgkmcnt(0)
	v_lshl_or_b32 v32, v25, 16, v24
	v_lshl_or_b32 v33, v27, 16, v26
	v_lshl_or_b32 v34, v29, 16, v28
	v_lshl_or_b32 v35, v31, 16, v30
	s_add_u32 s8, s2, 0x1600000
	s_addc_u32 s9, s3, 0
	global_store_dwordx4 v5, v[32:35], s[8:9]
	s_nop 1
	s_waitcnt vmcnt(7)
	ds_write_b128 v6, v[8:11] offset:0
	s_waitcnt lgkmcnt(0)
	s_barrier
	ds_read_u16 v24, v7 offset:0
	ds_read_u16 v25, v7 offset:144
	ds_read_u16 v26, v7 offset:288
	ds_read_u16 v27, v7 offset:432
	ds_read_u16 v28, v7 offset:576
	ds_read_u16 v29, v7 offset:720
	ds_read_u16 v30, v7 offset:864
	ds_read_u16 v31, v7 offset:1008
	s_waitcnt lgkmcnt(0)
	v_lshl_or_b32 v32, v25, 16, v24
	v_lshl_or_b32 v33, v27, 16, v26
	v_lshl_or_b32 v34, v29, 16, v28
	v_lshl_or_b32 v35, v31, 16, v30
	s_add_u32 s8, s2, 0x1800000
	s_addc_u32 s9, s3, 0
	global_store_dwordx4 v5, v[32:35], s[8:9]
	s_nop 1
	s_waitcnt vmcnt(6)
	ds_write_b128 v6, v[12:15] offset:9216
	s_waitcnt lgkmcnt(0)
	s_barrier
	ds_read_u16 v24, v7 offset:9216
	ds_read_u16 v25, v7 offset:9360
	ds_read_u16 v26, v7 offset:9504
	ds_read_u16 v27, v7 offset:9648
	ds_read_u16 v28, v7 offset:9792
	ds_read_u16 v29, v7 offset:9936
	ds_read_u16 v30, v7 offset:10080
	ds_read_u16 v31, v7 offset:10224
	s_waitcnt lgkmcnt(0)
	v_lshl_or_b32 v32, v25, 16, v24
	v_lshl_or_b32 v33, v27, 16, v26
	v_lshl_or_b32 v34, v29, 16, v28
	v_lshl_or_b32 v35, v31, 16, v30
	s_add_u32 s8, s2, 0x1a00000
	s_addc_u32 s9, s3, 0
	global_store_dwordx4 v5, v[32:35], s[8:9]
	s_nop 1
	s_waitcnt vmcnt(5)
	ds_write_b128 v6, v[16:19] offset:18432
	s_waitcnt lgkmcnt(0)
	s_barrier
	ds_read_u16 v24, v7 offset:18432
	ds_read_u16 v25, v7 offset:18576
	ds_read_u16 v26, v7 offset:18720
	ds_read_u16 v27, v7 offset:18864
	ds_read_u16 v28, v7 offset:19008
	ds_read_u16 v29, v7 offset:19152
	ds_read_u16 v30, v7 offset:19296
	ds_read_u16 v31, v7 offset:19440
	s_waitcnt lgkmcnt(0)
	v_lshl_or_b32 v32, v25, 16, v24
	v_lshl_or_b32 v33, v27, 16, v26
	v_lshl_or_b32 v34, v29, 16, v28
	v_lshl_or_b32 v35, v31, 16, v30
	s_add_u32 s8, s2, 0x1c00000
	s_addc_u32 s9, s3, 0
	global_store_dwordx4 v5, v[32:35], s[8:9]
	s_nop 1
	s_waitcnt vmcnt(4)
	ds_write_b128 v6, v[20:23] offset:27648
	s_waitcnt lgkmcnt(0)
	s_barrier
	ds_read_u16 v24, v7 offset:27648
	ds_read_u16 v25, v7 offset:27792
	ds_read_u16 v26, v7 offset:27936
	ds_read_u16 v27, v7 offset:28080
	ds_read_u16 v28, v7 offset:28224
	ds_read_u16 v29, v7 offset:28368
	ds_read_u16 v30, v7 offset:28512
	ds_read_u16 v31, v7 offset:28656
	s_waitcnt lgkmcnt(0)
	v_lshl_or_b32 v32, v25, 16, v24
	v_lshl_or_b32 v33, v27, 16, v26
	v_lshl_or_b32 v34, v29, 16, v28
	v_lshl_or_b32 v35, v31, 16, v30
	s_add_u32 s8, s2, 0x1e00000
	s_addc_u32 s9, s3, 0
	global_store_dwordx4 v5, v[32:35], s[8:9]
	s_nop 1
